# E53: E52 plus diff-attention K fragments of k-steps 1/2 prefetched at tile start into v[202:213] (constants re-materialized after the unit loop)
# baseline (speedup 1.0000x reference)
; template <int NQK>
; __device__ __forceinline__ void qkt_mi(f32x16& p0, f32x16& p1, const char* Ks, const bf16x8* qr, int r32, int hi, const f32x16& minit) {
;   constexpr int KROW = NQK * 32 + 16;
; #pragma unroll
;   for (int d0 = 0; d0 < NQK; ++d0) { const int cb = (d0 * 16 + hi * 8) * 2;
;     bf16x8 b0 = *reinterpret_cast<const bf16x8*>(Ks + r32 * KROW + cb);
;     bf16x8 b1 = *reinterpret_cast<const bf16x8*>(Ks + (32 + r32) * KROW + cb);
;     if (d0 == 0) { p0 = __builtin_amdgcn_mfma_f32_32x32x16_bf16(b0, qr[0], minit, 0, 0, 0); p1 = __builtin_amdgcn_mfma_f32_32x32x16_bf16(b1, qr[0], minit, 0, 0, 0); }
;     else { p0 = __builtin_amdgcn_mfma_f32_32x32x16_bf16(b0, qr[d0], p0, 0, 0, 0); p1 = __builtin_amdgcn_mfma_f32_32x32x16_bf16(b1, qr[d0], p1, 0, 0, 0); } }
; }
; __device__ __forceinline__ void decide_mi(f32x16& p0, f32x16& p1, f32x16& minit, float& M, float& alpha, const float thr2, const bool first) {
;   float pmax = p0[0];
; #pragma unroll
;   for (int r = 1; r < 16; ++r) pmax = fmaxf(pmax, p0[r]);
; #pragma unroll
;   for (int r = 0; r < 16; ++r) pmax = fmaxf(pmax, p1[r]);
;   { auto rr = __builtin_amdgcn_permlane32_swap(__float_as_uint(pmax), __float_as_uint(pmax), false, false);
;     pmax = fmaxf(__uint_as_float(rr[0]), __uint_as_float(rr[1])); }
;   if (__builtin_expect(!first && __all(pmax <= thr2), 1)) { alpha = 1.f; }
;   else { const float delta = first ? pmax : fmaxf(pmax, 0.f); alpha = first ? 1.f : __builtin_amdgcn_exp2f(-delta); M += delta;
; #pragma unroll
;     for (int r = 0; r < 16; ++r) { p0[r] -= delta; p1[r] -= delta; minit[r] = -M; } }
; }
.LBB0_1286:
	s_mov_b32 s15, s58
	s_mov_b32 s58, s8
	s_mul_i32 s8, s15, 0x2400
	v_add_u32_e32 v215, s8, v221
	ds_read_b128 v[232:235], v215 offset:53760
	ds_read_b128 v[112:115], v215 offset:49152
	ds_read_b128 v[236:239], v215 offset:49184
	ds_read_b128 v[202:205], v215 offset:53792
	ds_read_b128 v[206:209], v215 offset:53824
	ds_read_b128 v[210:213], v215 offset:49216
	v_exp_f32_e32 v96, v96
	v_exp_f32_e32 v97, v97
	v_exp_f32_e32 v99, v99
	s_waitcnt lgkmcnt(4)
	v_mfma_f32_32x32x16_bf16 v[128:143], v[112:115], v[146:149], v[80:95]
	s_waitcnt lgkmcnt(3)
	v_mfma_f32_32x32x16_bf16 v[128:143], v[236:239], v[150:153], v[128:143]
	v_exp_f32_e32 v100, v100
	v_exp_f32_e32 v101, v101
	v_exp_f32_e32 v102, v102
	v_exp_f32_e32 v103, v103
	v_mfma_f32_32x32x16_bf16 v[112:127], v[232:235], v[146:149], v[80:95]
	s_waitcnt lgkmcnt(2)
	v_mfma_f32_32x32x16_bf16 v[112:127], v[202:205], v[150:153], v[112:127]
	s_waitcnt lgkmcnt(0)
	v_mfma_f32_32x32x16_bf16 v[128:143], v[210:213], v[154:157], v[128:143]
	v_mfma_f32_32x32x16_bf16 v[112:127], v[206:209], v[154:157], v[112:127]
	ds_read_b128 v[232:235], v215 offset:53856
	ds_read_b128 v[236:239], v215 offset:49248
	v_exp_f32_e32 v215, v98
	v_exp_f32_e32 v98, v104
	v_exp_f32_e32 v104, v105
	v_exp_f32_e32 v105, v106
	v_exp_f32_e32 v106, v107
	v_exp_f32_e32 v107, v108
	v_exp_f32_e32 v108, v109
	v_exp_f32_e32 v109, v110
	v_exp_f32_e32 v110, v111
	v_add_f32_e32 v111, 0, v175
	v_add_f32_e32 v111, v176, v111
	v_add_f32_e32 v111, v177, v111
	v_add_f32_e32 v111, v178, v111
	v_add_f32_e32 v111, v179, v111
	v_add_f32_e32 v111, v181, v111
	v_add_f32_e32 v111, v183, v111
	v_add_f32_e32 v111, v185, v111
	v_add_f32_e32 v111, v180, v111
	v_add_f32_e32 v111, v182, v111
	v_add_f32_e32 v111, v184, v111
	v_add_f32_e32 v111, v227, v111
	v_add_f32_e32 v111, v228, v111
	v_add_f32_e32 v111, v229, v111
	v_add_f32_e32 v111, v230, v111
	v_add_f32_e32 v111, v174, v111
	v_add_f32_e32 v111, v96, v111
	v_add_f32_e32 v111, v97, v111
	v_add_f32_e32 v111, v215, v111
	v_add_f32_e32 v111, v99, v111
	v_add_f32_e32 v111, v100, v111
	v_add_f32_e32 v111, v101, v111
	v_add_f32_e32 v111, v102, v111
	s_waitcnt lgkmcnt(0)
	v_mfma_f32_32x32x16_bf16 v[128:143], v[236:239], v[158:161], v[128:143]
	v_add_f32_e32 v111, v103, v111
	v_add_f32_e32 v111, v98, v111
	v_add_f32_e32 v111, v104, v111
	v_add_f32_e32 v111, v105, v111
	v_add_f32_e32 v111, v106, v111
	v_add_f32_e32 v111, v107, v111
	v_add_f32_e32 v111, v108, v111
	v_add_f32_e32 v111, v109, v111
	v_add_f32_e32 v224, v110, v111
	s_nop 2
	v_max_f32_e32 v111, v129, v129
	v_max_f32_e32 v226, v128, v128
	v_mfma_f32_32x32x16_bf16 v[112:127], v[232:235], v[158:161], v[112:127]
	v_max_f32_e32 v111, v226, v111
	v_max3_f32 v111, v111, v130, v131
	v_max3_f32 v111, v111, v132, v133
	v_max3_f32 v111, v111, v134, v135
	v_max3_f32 v111, v111, v136, v137
	v_max3_f32 v111, v111, v138, v139
	v_max3_f32 v111, v111, v140, v141
	v_max3_f32 v111, v111, v142, v143
	s_nop 3
	v_max3_f32 v111, v111, v112, v113
	v_max3_f32 v111, v111, v114, v115
	v_max3_f32 v111, v111, v116, v117
	v_max3_f32 v111, v111, v118, v119
	v_max3_f32 v111, v111, v120, v121
	v_max3_f32 v111, v111, v122, v123
	v_max3_f32 v111, v111, v124, v125
	v_max3_f32 v111, v111, v126, v127
	v_mov_b32_e32 v226, v111
	s_nop 1
	v_permlane32_swap_b32_e32 v111, v226
	v_max_f32_e32 v226, v226, v226
	v_max_f32_e32 v111, v111, v111
	v_max_f32_e32 v111, v111, v226
	v_mov_b32_e32 v225, v224
	v_cmp_ge_f32_e32 vcc, s42, v111
	s_nop 0
	v_permlane32_swap_b32_e32 v224, v225
	s_cmp_eq_u64 vcc, exec
	s_cbranch_scc0 .LBB0_1301
	v_mov_b32_e32 v226, 1.0

; __device__ __forceinline__ void finishSM(f32x16& p0, f32x16& p1, float alpha, float& l_reg, bf16x8& pa0, bf16x8& pa1, bf16x8& pa2, bf16x8& pa3) {
; #pragma unroll
;   for (int r = 0; r < 16; ++r) p1[r] = __builtin_amdgcn_exp2f(p1[r]);
;   float ps = 0;
; #pragma unroll
;   for (int r = 0; r < 16; ++r) ps += p0[r];
; #pragma unroll
;   for (int r = 0; r < 16; ++r) ps += p1[r];
;   { auto rr = __builtin_amdgcn_permlane32_swap(__float_as_uint(ps), __float_as_uint(ps), false, false);
;     ps = __uint_as_float(rr[0]) + __uint_as_float(rr[1]); }
;   l_reg = l_reg * alpha + ps;
; template <int NQK>
; __device__ __forceinline__ void qkt_mi(f32x16& p0, f32x16& p1, const char* Ks, const bf16x8* qr, int r32, int hi, const f32x16& minit) {
;   constexpr int KROW = NQK * 32 + 16;
; #pragma unroll
;   for (int d0 = 0; d0 < NQK; ++d0) { const int cb = (d0 * 16 + hi * 8) * 2;
;     bf16x8 b0 = *reinterpret_cast<const bf16x8*>(Ks + r32 * KROW + cb);
;     bf16x8 b1 = *reinterpret_cast<const bf16x8*>(Ks + (32 + r32) * KROW + cb);
;     if (d0 == 0) { p0 = __builtin_amdgcn_mfma_f32_32x32x16_bf16(b0, qr[0], minit, 0, 0, 0); p1 = __builtin_amdgcn_mfma_f32_32x32x16_bf16(b1, qr[0], minit, 0, 0, 0); }
;     else { p0 = __builtin_amdgcn_mfma_f32_32x32x16_bf16(b0, qr[d0], p0, 0, 0, 0); p1 = __builtin_amdgcn_mfma_f32_32x32x16_bf16(b1, qr[d0], p1, 0, 0, 0); } }
; }
.LBB0_1292:
	v_exp_f32_e32 v227, v128
	v_exp_f32_e32 v229, v129
	v_exp_f32_e32 v230, v130
	v_exp_f32_e32 v233, v131
	v_exp_f32_e32 v234, v132
	v_exp_f32_e32 v237, v133
	v_exp_f32_e32 v238, v134
	v_exp_f32_e32 v241, v135
	v_exp_f32_e32 v228, v136
	v_exp_f32_e32 v231, v137
	v_exp_f32_e32 v232, v138
	v_exp_f32_e32 v235, v139
	v_exp_f32_e32 v236, v140
	v_exp_f32_e32 v239, v141
	v_exp_f32_e32 v240, v142
	v_exp_f32_e32 v242, v143
	s_waitcnt lgkmcnt(0)
	s_barrier
	v_add_u32_e32 v243, s11, v221
	ds_read_b128 v[244:247], v243 offset:53760
	ds_read_b128 v[96:99], v243 offset:49152
	ds_read_b128 v[248:251], v243 offset:49184
	ds_read_b128 v[202:205], v243 offset:53792
	ds_read_b128 v[206:209], v243 offset:53824
	ds_read_b128 v[210:213], v243 offset:49216
	v_exp_f32_e32 v115, v115
	v_exp_f32_e32 v119, v119
	s_waitcnt lgkmcnt(4)
	v_mfma_f32_32x32x16_bf16 v[128:143], v[96:99], v[146:149], v[64:79]
	v_mfma_f32_32x32x16_bf16 v[96:111], v[244:247], v[146:149], v[64:79]
	s_waitcnt lgkmcnt(3)
	v_mfma_f32_32x32x16_bf16 v[128:143], v[248:251], v[150:153], v[128:143]
	s_waitcnt lgkmcnt(2)
	v_mfma_f32_32x32x16_bf16 v[96:111], v[202:205], v[150:153], v[96:111]
	s_waitcnt lgkmcnt(0)
	v_mfma_f32_32x32x16_bf16 v[128:143], v[210:213], v[154:157], v[128:143]
	v_mfma_f32_32x32x16_bf16 v[96:111], v[206:209], v[154:157], v[96:111]
	ds_read_b128 v[244:247], v243 offset:53856
	ds_read_b128 v[248:251], v243 offset:49248
	v_exp_f32_e32 v243, v112
	v_add_f32_e32 v112, 0, v227
	v_add_f32_e32 v112, v229, v112
	v_add_f32_e32 v112, v230, v112
	v_add_f32_e32 v112, v233, v112
	v_add_f32_e32 v112, v234, v112
	v_add_f32_e32 v112, v237, v112
	v_add_f32_e32 v112, v238, v112
	v_add_f32_e32 v112, v241, v112
	v_add_f32_e32 v112, v228, v112
	v_add_f32_e32 v112, v231, v112
	v_add_f32_e32 v112, v232, v112
	v_add_f32_e32 v112, v235, v112
	v_add_f32_e32 v112, v236, v112
	s_waitcnt lgkmcnt(1)
	v_mfma_f32_32x32x16_bf16 v[96:111], v[244:247], v[158:161], v[96:111]
	v_exp_f32_e32 v244, v113
	v_add_f32_e32 v112, v239, v112
	v_exp_f32_e32 v245, v114
	v_add_f32_e32 v112, v240, v112
	v_add_f32_e32 v112, v242, v112
	v_exp_f32_e32 v246, v116
	v_add_f32_e32 v112, v243, v112
	v_exp_f32_e32 v247, v117
	v_add_f32_e32 v112, v244, v112
	s_waitcnt lgkmcnt(0)
	v_mfma_f32_32x32x16_bf16 v[128:143], v[248:251], v[158:161], v[128:143]
	v_exp_f32_e32 v248, v118
	v_add_f32_e32 v112, v245, v112
	v_add_f32_e32 v112, v115, v112
	v_exp_f32_e32 v116, v120
	v_add_f32_e32 v112, v246, v112
	v_exp_f32_e32 v117, v121
	v_add_f32_e32 v112, v247, v112
	v_exp_f32_e32 v118, v122
	v_add_f32_e32 v112, v248, v112
	v_exp_f32_e32 v120, v123
	v_add_f32_e32 v112, v119, v112
	v_exp_f32_e32 v121, v124
	v_add_f32_e32 v112, v116, v112
	v_exp_f32_e32 v122, v125
	v_add_f32_e32 v112, v117, v112
	v_exp_f32_e32 v123, v126
	v_add_f32_e32 v112, v118, v112
	v_exp_f32_e32 v124, v127
	v_add_f32_e32 v112, v120, v112
	v_add_f32_e32 v112, v121, v112
	v_add_f32_e32 v112, v122, v112
	v_add_f32_e32 v112, v123, v112
	v_add_f32_e32 v113, v124, v112
	v_max_f32_e32 v112, v129, v129
	v_max_f32_e32 v125, v128, v128
	v_max_f32_e32 v112, v125, v112
	v_max3_f32 v112, v112, v130, v131
	v_max3_f32 v112, v112, v132, v133
	v_max3_f32 v112, v112, v134, v135
	v_max3_f32 v112, v112, v136, v137
	v_max3_f32 v112, v112, v138, v139
	v_max3_f32 v112, v112, v140, v141
	v_max3_f32 v112, v112, v142, v143
	v_max3_f32 v112, v112, v96, v97
	v_max3_f32 v112, v112, v98, v99
	v_max3_f32 v112, v112, v100, v101
	v_max3_f32 v112, v112, v102, v103
	v_max3_f32 v112, v112, v104, v105
	v_max3_f32 v112, v112, v106, v107
	v_max3_f32 v112, v112, v108, v109
	v_max3_f32 v112, v112, v110, v111
	v_mov_b32_e32 v125, v112
	s_nop 1
	v_permlane32_swap_b32_e32 v112, v125
	v_max_f32_e32 v125, v125, v125
	v_max_f32_e32 v112, v112, v112
	v_max_f32_e32 v125, v112, v125
	v_mov_b32_e32 v114, v113
	v_cmp_ge_f32_e32 vcc, s42, v125
	s_nop 0
	v_permlane32_swap_b32_e32 v113, v114
	v_mov_b32_e32 v112, 1.0
	s_cmp_eq_u64 vcc, exec
	s_cbranch_scc0 .LBB0_1302

; #define LAS __attribute__((address_space(3)))
; __device__ __forceinline__ unsigned xb_add(unsigned* p, unsigned v) { return __hip_atomic_fetch_add(p, v, __ATOMIC_RELAXED, __HIP_MEMORY_SCOPE_AGENT); }
; __device__ __forceinline__ unsigned xb_xcc_id() { return (unsigned)__builtin_amdgcn_s_getreg((3 << 11) | 20) & 0xFu; }
; __device__ __forceinline__ void grid_sync(unsigned* bar, volatile LAS unsigned* st) {
;   asm volatile("s_waitcnt vmcnt(0)" ::: "memory");
;   __syncthreads();
;   if (threadIdx.x == 0) {
;     __builtin_amdgcn_s_waitcnt(0);
;     const unsigned x = xb_xcc_id();
;     unsigned nloc = st[0], nx = st[1];
;     if (nloc == 0u) { xcd_barrier_complete(bar, x, nloc, nx); st[0] = nloc; st[1] = nx; }
;     const unsigned old = xb_add(&bar[XB_XSUB(x)], 1u);
;     const unsigned gen = old / nloc;
.LBB0_1314:
	s_mov_b64 s[8:9], exec
	s_mov_b64 exec, -1
	v_mov_b32_e32 v202, 0x1000
	v_mov_b32_e32 v203, 0x2000
	v_mov_b32_e32 v204, 0x9bcd000
	v_mov_b32_e32 v205, 1
	v_mov_b32_e32 v206, 0x3ecc95a3
	v_mov_b32_e32 v207, 0x9bca000
	v_mov_b32_e32 v208, 0x7f800000
	v_mov_b32_e32 v209, 0xff
	v_mov_b32_e32 v210, 0x41ff
	v_mov_b32_e32 v212, 0x41b17218
	v_mov_b32_e32 v213, 0xf149f2ca
	v_mbcnt_lo_u32_b32 v211, -1, 0
	v_mbcnt_hi_u32_b32 v211, -1, v211
	s_mov_b64 exec, s[8:9]
	s_mov_b64 s[8:9], s[0:1]
	s_waitcnt vmcnt(0)
	s_barrier
	s_mov_b64 s[6:7], exec
	v_readlane_b32 s10, v255, 17
	v_readlane_b32 s11, v255, 18
	v_readlane_b32 s68, v255, 20
	v_readlane_b32 s44, v255, 32
	s_and_b64 s[10:11], s[6:7], s[10:11]
	s_movk_i32 s90, 0x300
	s_movk_i32 s91, 0x60
	s_mov_b32 s88, 0x30000
	s_mov_b32 s89, 0xe000
	s_movk_i32 s40, 0x70
	s_movk_i32 s41, 0x50
	v_readlane_b32 s69, v255, 21
	v_readlane_b32 s45, v255, 33
	s_mov_b64 exec, s[10:11]
	s_cbranch_execz .LBB0_1367
	s_load_dwordx2 s[8:9], s[8:9], 0xd8
	s_waitcnt vmcnt(0) expcnt(0) lgkmcnt(0)
	s_getreg_b32 s10, hwreg(HW_REG_XCC_ID, 0, 4)
	ds_read_b32 v2, v144
	ds_read_b32 v0, v144 offset:4
	s_and_b32 s51, s10, 15
	s_waitcnt lgkmcnt(1)
	v_cmp_ne_u32_e32 vcc, 0, v2
	s_cbranch_vccnz .LBB0_1331
	s_add_u32 s10, s8, 0x9bca300
	s_addc_u32 s11, s9, 0
	s_add_u32 s12, s8, 0x9bca500
	s_addc_u32 s13, s9, 0
	s_add_u32 s14, s8, 0x9bca600
	s_addc_u32 s15, s9, 0
	s_add_u32 s16, s8, 0x9bca700
	s_addc_u32 s17, s9, 0
	s_add_u32 s18, s8, 0x9bca800
	s_addc_u32 s19, s9, 0
	s_add_u32 s20, s8, 0x9bca900
	s_addc_u32 s21, s9, 0
	s_add_u32 s22, s8, 0x9bcaa00
	s_addc_u32 s23, s9, 0
	s_add_u32 s28, s8, 0x9bcab00
	s_addc_u32 s29, s9, 0
	s_add_u32 s36, s8, 0x9bcac00
	s_addc_u32 s37, s9, 0
	s_add_u32 s38, s8, 0x9bcad00
	s_addc_u32 s39, s9, 0
	s_add_u32 s84, s8, 0x9bcae00
	s_addc_u32 s85, s9, 0
	s_add_u32 s68, s8, 0x9bcaf00
	s_addc_u32 s69, s9, 0
	s_add_u32 s74, s8, 0x9bcb000
	s_addc_u32 s75, s9, 0
	s_add_u32 s44, s8, 0x9bcb100
	s_addc_u32 s45, s9, 0
	s_add_u32 s58, s8, 0x9bcb200
	s_addc_u32 s59, s9, 0
	s_add_u32 s86, s8, 0x9bcb300
	s_addc_u32 s87, s9, 0
	s_add_u32 s88, s8, 0x9bcb400
	s_addc_u32 s89, s9, 0
	s_mov_b32 s76, 1
	s_branch .LBB0_1319
